# P8 row pass rewritten by hand (same scheme as P4): gain vector loaded once, all row loads up front, f32 nontemporal stores never waited
# speedup vs baseline: 1.2554x; 1.0040x over previous
.LBB0_753:
	s_or_b64 exec, exec, s[0:1]
	s_and_b64 vcc, exec, s[80:81]
	s_waitcnt lgkmcnt(0)
	s_barrier
	s_cbranch_vccnz .LBB0_756
	v_and_b32_e32 v1, 63, v214
	v_readlane_b32 s22, v244, 10
	v_readlane_b32 s23, v244, 11
	v_lshlrev_b32_e32 v2, 3, v1
	v_lshlrev_b32_e32 v5, 4, v1
	v_add_u32_e32 v3, 0x16800000, v2
	v_mov_b32_e32 v4, v5
	v_mov_b32_e32 v143, 0x358637bd
	s_nop 2
	global_load_dwordx4 v[80:83], v5, s[22:23] offset:0
	global_load_dwordx4 v[84:87], v5, s[22:23] offset:1024
	global_load_dwordx4 v[88:91], v5, s[22:23] offset:2048
	global_load_dwordx4 v[92:95], v5, s[22:23] offset:3072
	s_lshl_b32 s5, s66, 3
	s_mov_b32 s35, s68
.Lp8_loop:
	s_mov_b32 s0, s35
	s_lshl_b32 s1, s0, 11
	s_add_u32 s8, s76, s1
	s_addc_u32 s9, s77, 0
	s_lshl_b32 s1, s0, 12
	s_add_u32 s36, s72, s1
	s_addc_u32 s37, s73, 0
	global_load_dwordx2 v[16:17], v2, s[8:9] offset:0 nt
	global_load_dwordx2 v[18:19], v2, s[8:9] offset:512 nt
	global_load_dwordx2 v[20:21], v2, s[8:9] offset:1024 nt
	global_load_dwordx2 v[22:23], v2, s[8:9] offset:1536 nt
	global_load_dwordx2 v[24:25], v3, s[8:9] offset:0 nt
	global_load_dwordx2 v[26:27], v3, s[8:9] offset:512 nt
	global_load_dwordx2 v[28:29], v3, s[8:9] offset:1024 nt
	global_load_dwordx2 v[30:31], v3, s[8:9] offset:1536 nt
	s_mul_i32 s0, s5, 1
	s_add_i32 s0, s0, s35
	s_lshl_b32 s1, s0, 11
	s_add_u32 s10, s76, s1
	s_addc_u32 s11, s77, 0
	s_lshl_b32 s1, s0, 12
	s_add_u32 s38, s72, s1
	s_addc_u32 s39, s73, 0
	global_load_dwordx2 v[32:33], v2, s[10:11] offset:0 nt
	global_load_dwordx2 v[34:35], v2, s[10:11] offset:512 nt
	global_load_dwordx2 v[36:37], v2, s[10:11] offset:1024 nt
	global_load_dwordx2 v[38:39], v2, s[10:11] offset:1536 nt
	global_load_dwordx2 v[40:41], v3, s[10:11] offset:0 nt
	global_load_dwordx2 v[42:43], v3, s[10:11] offset:512 nt
	global_load_dwordx2 v[44:45], v3, s[10:11] offset:1024 nt
	global_load_dwordx2 v[46:47], v3, s[10:11] offset:1536 nt
	s_mul_i32 s0, s5, 2
	s_add_i32 s0, s0, s35
	s_lshl_b32 s1, s0, 11
	s_add_u32 s12, s76, s1
	s_addc_u32 s13, s77, 0
	s_lshl_b32 s1, s0, 12
	s_add_u32 s40, s72, s1
	s_addc_u32 s41, s73, 0
	global_load_dwordx2 v[48:49], v2, s[12:13] offset:0 nt
	global_load_dwordx2 v[50:51], v2, s[12:13] offset:512 nt
	global_load_dwordx2 v[52:53], v2, s[12:13] offset:1024 nt
	global_load_dwordx2 v[54:55], v2, s[12:13] offset:1536 nt
	global_load_dwordx2 v[56:57], v3, s[12:13] offset:0 nt
	global_load_dwordx2 v[58:59], v3, s[12:13] offset:512 nt
	global_load_dwordx2 v[60:61], v3, s[12:13] offset:1024 nt
	global_load_dwordx2 v[62:63], v3, s[12:13] offset:1536 nt
	s_mul_i32 s0, s5, 3
	s_add_i32 s0, s0, s35
	s_lshl_b32 s1, s0, 11
	s_add_u32 s16, s76, s1
	s_addc_u32 s17, s77, 0
	s_lshl_b32 s1, s0, 12
	s_add_u32 s42, s72, s1
	s_addc_u32 s43, s73, 0
	global_load_dwordx2 v[64:65], v2, s[16:17] offset:0 nt
	global_load_dwordx2 v[66:67], v2, s[16:17] offset:512 nt
	global_load_dwordx2 v[68:69], v2, s[16:17] offset:1024 nt
	global_load_dwordx2 v[70:71], v2, s[16:17] offset:1536 nt
	global_load_dwordx2 v[72:73], v3, s[16:17] offset:0 nt
	global_load_dwordx2 v[74:75], v3, s[16:17] offset:512 nt
	global_load_dwordx2 v[76:77], v3, s[16:17] offset:1024 nt
	global_load_dwordx2 v[78:79], v3, s[16:17] offset:1536 nt
	s_waitcnt vmcnt(24)
	v_lshlrev_b32_e32 v96, 16, v16
	v_and_b32_e32 v97, 0xffff0000, v16
	v_lshlrev_b32_e32 v98, 16, v17
	v_and_b32_e32 v99, 0xffff0000, v17
	v_lshlrev_b32_e32 v100, 16, v18
	v_and_b32_e32 v101, 0xffff0000, v18
	v_lshlrev_b32_e32 v102, 16, v19
	v_and_b32_e32 v103, 0xffff0000, v19
	v_lshlrev_b32_e32 v104, 16, v20
	v_and_b32_e32 v105, 0xffff0000, v20
	v_lshlrev_b32_e32 v106, 16, v21
	v_and_b32_e32 v107, 0xffff0000, v21
	v_lshlrev_b32_e32 v108, 16, v22
	v_and_b32_e32 v109, 0xffff0000, v22
	v_lshlrev_b32_e32 v110, 16, v23
	v_and_b32_e32 v111, 0xffff0000, v23
	v_mul_f32_e32 v129, v97, v97
	v_mul_f32_e32 v130, v99, v99
	v_fmac_f32_e32 v129, v96, v96
	v_fmac_f32_e32 v130, v98, v98
	v_add_f32_e32 v128, v129, v130
	v_mul_f32_e32 v129, v101, v101
	v_mul_f32_e32 v130, v103, v103
	v_fmac_f32_e32 v129, v100, v100
	v_fmac_f32_e32 v130, v102, v102
	v_add_f32_e32 v129, v129, v130
	v_add_f32_e32 v128, v128, v129
	v_mul_f32_e32 v129, v105, v105
	v_mul_f32_e32 v130, v107, v107
	v_fmac_f32_e32 v129, v104, v104
	v_fmac_f32_e32 v130, v106, v106
	v_add_f32_e32 v129, v129, v130
	v_add_f32_e32 v128, v128, v129
	v_mul_f32_e32 v129, v109, v109
	v_mul_f32_e32 v130, v111, v111
	v_fmac_f32_e32 v129, v108, v108
	v_fmac_f32_e32 v130, v110, v110
	v_add_f32_e32 v129, v129, v130
	v_add_f32_e32 v128, v128, v129
	v_lshlrev_b32_e32 v112, 16, v24
	v_and_b32_e32 v113, 0xffff0000, v24
	v_lshlrev_b32_e32 v114, 16, v25
	v_and_b32_e32 v115, 0xffff0000, v25
	v_lshlrev_b32_e32 v116, 16, v26
	v_and_b32_e32 v117, 0xffff0000, v26
	v_lshlrev_b32_e32 v118, 16, v27
	v_and_b32_e32 v119, 0xffff0000, v27
	v_lshlrev_b32_e32 v120, 16, v28
	v_and_b32_e32 v121, 0xffff0000, v28
	v_lshlrev_b32_e32 v122, 16, v29
	v_and_b32_e32 v123, 0xffff0000, v29
	v_lshlrev_b32_e32 v124, 16, v30
	v_and_b32_e32 v125, 0xffff0000, v30
	v_lshlrev_b32_e32 v126, 16, v31
	v_and_b32_e32 v127, 0xffff0000, v31
	v_add_f32_dpp v128, v128, v128 quad_perm:[1,0,3,2] row_mask:0xf bank_mask:0xf
	s_nop 1
	v_add_f32_dpp v128, v128, v128 quad_perm:[2,3,0,1] row_mask:0xf bank_mask:0xf
	s_nop 1
	v_add_f32_dpp v128, v128, v128 row_half_mirror row_mask:0xf bank_mask:0xf
	s_nop 1
	v_add_f32_dpp v128, v128, v128 row_mirror row_mask:0xf bank_mask:0xf
	s_nop 0
	v_readlane_b32 s24, v128, 0
	v_readlane_b32 s25, v128, 16
	v_readlane_b32 s26, v128, 32
	v_readlane_b32 s27, v128, 48
	v_mov_b32_e32 v129, s24
	v_mov_b32_e32 v130, s26
	v_add_f32_e32 v129, s25, v129
	v_add_f32_e32 v130, s27, v130
	v_add_f32_e32 v128, v129, v130
	v_fmamk_f32 v128, v128, 0x3a800000, v143
	v_sqrt_f32_e32 v132, v128
	s_nop 0
	v_add_u32_e32 v133, -1, v132
	v_add_u32_e32 v134, 1, v132
	v_fma_f32 v135, -v133, v132, v128
	v_fma_f32 v136, -v134, v132, v128
	v_cmp_ge_f32_e64 s[20:21], 0, v135
	s_nop 1
	v_cndmask_b32_e64 v132, v132, v133, s[20:21]
	v_cmp_lt_f32_e64 s[20:21], 0, v136
	s_nop 1
	v_cndmask_b32_e64 v132, v132, v134, s[20:21]
	v_div_scale_f32 v133, s[20:21], v132, v132, 1.0
	v_rcp_f32_e32 v134, v133
	v_div_scale_f32 v135, vcc, 1.0, v132, 1.0
	v_fma_f32 v136, -v133, v134, 1.0
	v_fmac_f32_e32 v134, v136, v134
	v_mul_f32_e32 v136, v135, v134
	v_fma_f32 v137, -v133, v136, v135
	v_fmac_f32_e32 v136, v137, v134
	v_fma_f32 v133, -v133, v136, v135
	s_nop 1
	v_div_fmas_f32 v133, v133, v134, v136
	v_div_fixup_f32 v128, v133, v132, 1.0
	v_pk_mul_f32 v[96:97], v[96:97], v[128:129] op_sel_hi:[1,0]
	v_pk_mul_f32 v[98:99], v[98:99], v[128:129] op_sel_hi:[1,0]
	v_pk_mul_f32 v[100:101], v[100:101], v[128:129] op_sel_hi:[1,0]
	v_pk_mul_f32 v[102:103], v[102:103], v[128:129] op_sel_hi:[1,0]
	v_pk_mul_f32 v[104:105], v[104:105], v[128:129] op_sel_hi:[1,0]
	v_pk_mul_f32 v[106:107], v[106:107], v[128:129] op_sel_hi:[1,0]
	v_pk_mul_f32 v[108:109], v[108:109], v[128:129] op_sel_hi:[1,0]
	v_pk_mul_f32 v[110:111], v[110:111], v[128:129] op_sel_hi:[1,0]
	v_pk_fma_f32 v[112:113], v[80:81], v[96:97], v[112:113]
	v_pk_fma_f32 v[114:115], v[82:83], v[98:99], v[114:115]
	v_pk_fma_f32 v[116:117], v[84:85], v[100:101], v[116:117]
	v_pk_fma_f32 v[118:119], v[86:87], v[102:103], v[118:119]
	v_pk_fma_f32 v[120:121], v[88:89], v[104:105], v[120:121]
	v_pk_fma_f32 v[122:123], v[90:91], v[106:107], v[122:123]
	v_pk_fma_f32 v[124:125], v[92:93], v[108:109], v[124:125]
	v_pk_fma_f32 v[126:127], v[94:95], v[110:111], v[126:127]
	global_store_dwordx4 v4, v[112:115], s[36:37] offset:0 nt
	global_store_dwordx4 v4, v[116:119], s[36:37] offset:1024 nt
	global_store_dwordx4 v4, v[120:123], s[36:37] offset:2048 nt
	global_store_dwordx4 v4, v[124:127], s[36:37] offset:3072 nt
	s_waitcnt vmcnt(20)
	v_lshlrev_b32_e32 v96, 16, v32
	v_and_b32_e32 v97, 0xffff0000, v32
	v_lshlrev_b32_e32 v98, 16, v33
	v_and_b32_e32 v99, 0xffff0000, v33
	v_lshlrev_b32_e32 v100, 16, v34
	v_and_b32_e32 v101, 0xffff0000, v34
	v_lshlrev_b32_e32 v102, 16, v35
	v_and_b32_e32 v103, 0xffff0000, v35
	v_lshlrev_b32_e32 v104, 16, v36
	v_and_b32_e32 v105, 0xffff0000, v36
	v_lshlrev_b32_e32 v106, 16, v37
	v_and_b32_e32 v107, 0xffff0000, v37
	v_lshlrev_b32_e32 v108, 16, v38
	v_and_b32_e32 v109, 0xffff0000, v38
	v_lshlrev_b32_e32 v110, 16, v39
	v_and_b32_e32 v111, 0xffff0000, v39
	v_mul_f32_e32 v129, v97, v97
	v_mul_f32_e32 v130, v99, v99
	v_fmac_f32_e32 v129, v96, v96
	v_fmac_f32_e32 v130, v98, v98
	v_add_f32_e32 v128, v129, v130
	v_mul_f32_e32 v129, v101, v101
	v_mul_f32_e32 v130, v103, v103
	v_fmac_f32_e32 v129, v100, v100
	v_fmac_f32_e32 v130, v102, v102
	v_add_f32_e32 v129, v129, v130
	v_add_f32_e32 v128, v128, v129
	v_mul_f32_e32 v129, v105, v105
	v_mul_f32_e32 v130, v107, v107
	v_fmac_f32_e32 v129, v104, v104
	v_fmac_f32_e32 v130, v106, v106
	v_add_f32_e32 v129, v129, v130
	v_add_f32_e32 v128, v128, v129
	v_mul_f32_e32 v129, v109, v109
	v_mul_f32_e32 v130, v111, v111
	v_fmac_f32_e32 v129, v108, v108
	v_fmac_f32_e32 v130, v110, v110
	v_add_f32_e32 v129, v129, v130
	v_add_f32_e32 v128, v128, v129
	v_lshlrev_b32_e32 v112, 16, v40
	v_and_b32_e32 v113, 0xffff0000, v40
	v_lshlrev_b32_e32 v114, 16, v41
	v_and_b32_e32 v115, 0xffff0000, v41
	v_lshlrev_b32_e32 v116, 16, v42
	v_and_b32_e32 v117, 0xffff0000, v42
	v_lshlrev_b32_e32 v118, 16, v43
	v_and_b32_e32 v119, 0xffff0000, v43
	v_lshlrev_b32_e32 v120, 16, v44
	v_and_b32_e32 v121, 0xffff0000, v44
	v_lshlrev_b32_e32 v122, 16, v45
	v_and_b32_e32 v123, 0xffff0000, v45
	v_lshlrev_b32_e32 v124, 16, v46
	v_and_b32_e32 v125, 0xffff0000, v46
	v_lshlrev_b32_e32 v126, 16, v47
	v_and_b32_e32 v127, 0xffff0000, v47
	v_add_f32_dpp v128, v128, v128 quad_perm:[1,0,3,2] row_mask:0xf bank_mask:0xf
	s_nop 1
	v_add_f32_dpp v128, v128, v128 quad_perm:[2,3,0,1] row_mask:0xf bank_mask:0xf
	s_nop 1
	v_add_f32_dpp v128, v128, v128 row_half_mirror row_mask:0xf bank_mask:0xf
	s_nop 1
	v_add_f32_dpp v128, v128, v128 row_mirror row_mask:0xf bank_mask:0xf
	s_nop 0
	v_readlane_b32 s24, v128, 0
	v_readlane_b32 s25, v128, 16
	v_readlane_b32 s26, v128, 32
	v_readlane_b32 s27, v128, 48
	v_mov_b32_e32 v129, s24
	v_mov_b32_e32 v130, s26
	v_add_f32_e32 v129, s25, v129
	v_add_f32_e32 v130, s27, v130
	v_add_f32_e32 v128, v129, v130
	v_fmamk_f32 v128, v128, 0x3a800000, v143
	v_sqrt_f32_e32 v132, v128
	s_nop 0
	v_add_u32_e32 v133, -1, v132
	v_add_u32_e32 v134, 1, v132
	v_fma_f32 v135, -v133, v132, v128
	v_fma_f32 v136, -v134, v132, v128
	v_cmp_ge_f32_e64 s[20:21], 0, v135
	s_nop 1
	v_cndmask_b32_e64 v132, v132, v133, s[20:21]
	v_cmp_lt_f32_e64 s[20:21], 0, v136
	s_nop 1
	v_cndmask_b32_e64 v132, v132, v134, s[20:21]
	v_div_scale_f32 v133, s[20:21], v132, v132, 1.0
	v_rcp_f32_e32 v134, v133
	v_div_scale_f32 v135, vcc, 1.0, v132, 1.0
	v_fma_f32 v136, -v133, v134, 1.0
	v_fmac_f32_e32 v134, v136, v134
	v_mul_f32_e32 v136, v135, v134
	v_fma_f32 v137, -v133, v136, v135
	v_fmac_f32_e32 v136, v137, v134
	v_fma_f32 v133, -v133, v136, v135
	s_nop 1
	v_div_fmas_f32 v133, v133, v134, v136
	v_div_fixup_f32 v128, v133, v132, 1.0
	v_pk_mul_f32 v[96:97], v[96:97], v[128:129] op_sel_hi:[1,0]
	v_pk_mul_f32 v[98:99], v[98:99], v[128:129] op_sel_hi:[1,0]
	v_pk_mul_f32 v[100:101], v[100:101], v[128:129] op_sel_hi:[1,0]
	v_pk_mul_f32 v[102:103], v[102:103], v[128:129] op_sel_hi:[1,0]
	v_pk_mul_f32 v[104:105], v[104:105], v[128:129] op_sel_hi:[1,0]
	v_pk_mul_f32 v[106:107], v[106:107], v[128:129] op_sel_hi:[1,0]
	v_pk_mul_f32 v[108:109], v[108:109], v[128:129] op_sel_hi:[1,0]
	v_pk_mul_f32 v[110:111], v[110:111], v[128:129] op_sel_hi:[1,0]
	v_pk_fma_f32 v[112:113], v[80:81], v[96:97], v[112:113]
	v_pk_fma_f32 v[114:115], v[82:83], v[98:99], v[114:115]
	v_pk_fma_f32 v[116:117], v[84:85], v[100:101], v[116:117]
	v_pk_fma_f32 v[118:119], v[86:87], v[102:103], v[118:119]
	v_pk_fma_f32 v[120:121], v[88:89], v[104:105], v[120:121]
	v_pk_fma_f32 v[122:123], v[90:91], v[106:107], v[122:123]
	v_pk_fma_f32 v[124:125], v[92:93], v[108:109], v[124:125]
	v_pk_fma_f32 v[126:127], v[94:95], v[110:111], v[126:127]
	global_store_dwordx4 v4, v[112:115], s[38:39] offset:0 nt
	global_store_dwordx4 v4, v[116:119], s[38:39] offset:1024 nt
	global_store_dwordx4 v4, v[120:123], s[38:39] offset:2048 nt
	global_store_dwordx4 v4, v[124:127], s[38:39] offset:3072 nt
	s_waitcnt vmcnt(16)
	v_lshlrev_b32_e32 v96, 16, v48
	v_and_b32_e32 v97, 0xffff0000, v48
	v_lshlrev_b32_e32 v98, 16, v49
	v_and_b32_e32 v99, 0xffff0000, v49
	v_lshlrev_b32_e32 v100, 16, v50
	v_and_b32_e32 v101, 0xffff0000, v50
	v_lshlrev_b32_e32 v102, 16, v51
	v_and_b32_e32 v103, 0xffff0000, v51
	v_lshlrev_b32_e32 v104, 16, v52
	v_and_b32_e32 v105, 0xffff0000, v52
	v_lshlrev_b32_e32 v106, 16, v53
	v_and_b32_e32 v107, 0xffff0000, v53
	v_lshlrev_b32_e32 v108, 16, v54
	v_and_b32_e32 v109, 0xffff0000, v54
	v_lshlrev_b32_e32 v110, 16, v55
	v_and_b32_e32 v111, 0xffff0000, v55
	v_mul_f32_e32 v129, v97, v97
	v_mul_f32_e32 v130, v99, v99
	v_fmac_f32_e32 v129, v96, v96
	v_fmac_f32_e32 v130, v98, v98
	v_add_f32_e32 v128, v129, v130
	v_mul_f32_e32 v129, v101, v101
	v_mul_f32_e32 v130, v103, v103
	v_fmac_f32_e32 v129, v100, v100
	v_fmac_f32_e32 v130, v102, v102
	v_add_f32_e32 v129, v129, v130
	v_add_f32_e32 v128, v128, v129
	v_mul_f32_e32 v129, v105, v105
	v_mul_f32_e32 v130, v107, v107
	v_fmac_f32_e32 v129, v104, v104
	v_fmac_f32_e32 v130, v106, v106
	v_add_f32_e32 v129, v129, v130
	v_add_f32_e32 v128, v128, v129
	v_mul_f32_e32 v129, v109, v109
	v_mul_f32_e32 v130, v111, v111
	v_fmac_f32_e32 v129, v108, v108
	v_fmac_f32_e32 v130, v110, v110
	v_add_f32_e32 v129, v129, v130
	v_add_f32_e32 v128, v128, v129
	v_lshlrev_b32_e32 v112, 16, v56
	v_and_b32_e32 v113, 0xffff0000, v56
	v_lshlrev_b32_e32 v114, 16, v57
	v_and_b32_e32 v115, 0xffff0000, v57
	v_lshlrev_b32_e32 v116, 16, v58
	v_and_b32_e32 v117, 0xffff0000, v58
	v_lshlrev_b32_e32 v118, 16, v59
	v_and_b32_e32 v119, 0xffff0000, v59
	v_lshlrev_b32_e32 v120, 16, v60
	v_and_b32_e32 v121, 0xffff0000, v60
	v_lshlrev_b32_e32 v122, 16, v61
	v_and_b32_e32 v123, 0xffff0000, v61
	v_lshlrev_b32_e32 v124, 16, v62
	v_and_b32_e32 v125, 0xffff0000, v62
	v_lshlrev_b32_e32 v126, 16, v63
	v_and_b32_e32 v127, 0xffff0000, v63
	v_add_f32_dpp v128, v128, v128 quad_perm:[1,0,3,2] row_mask:0xf bank_mask:0xf
	s_nop 1
	v_add_f32_dpp v128, v128, v128 quad_perm:[2,3,0,1] row_mask:0xf bank_mask:0xf
	s_nop 1
	v_add_f32_dpp v128, v128, v128 row_half_mirror row_mask:0xf bank_mask:0xf
	s_nop 1
	v_add_f32_dpp v128, v128, v128 row_mirror row_mask:0xf bank_mask:0xf
	s_nop 0
	v_readlane_b32 s24, v128, 0
	v_readlane_b32 s25, v128, 16
	v_readlane_b32 s26, v128, 32
	v_readlane_b32 s27, v128, 48
	v_mov_b32_e32 v129, s24
	v_mov_b32_e32 v130, s26
	v_add_f32_e32 v129, s25, v129
	v_add_f32_e32 v130, s27, v130
	v_add_f32_e32 v128, v129, v130
	v_fmamk_f32 v128, v128, 0x3a800000, v143
	v_sqrt_f32_e32 v132, v128
	s_nop 0
	v_add_u32_e32 v133, -1, v132
	v_add_u32_e32 v134, 1, v132
	v_fma_f32 v135, -v133, v132, v128
	v_fma_f32 v136, -v134, v132, v128
	v_cmp_ge_f32_e64 s[20:21], 0, v135
	s_nop 1
	v_cndmask_b32_e64 v132, v132, v133, s[20:21]
	v_cmp_lt_f32_e64 s[20:21], 0, v136
	s_nop 1
	v_cndmask_b32_e64 v132, v132, v134, s[20:21]
	v_div_scale_f32 v133, s[20:21], v132, v132, 1.0
	v_rcp_f32_e32 v134, v133
	v_div_scale_f32 v135, vcc, 1.0, v132, 1.0
	v_fma_f32 v136, -v133, v134, 1.0
	v_fmac_f32_e32 v134, v136, v134
	v_mul_f32_e32 v136, v135, v134
	v_fma_f32 v137, -v133, v136, v135
	v_fmac_f32_e32 v136, v137, v134
	v_fma_f32 v133, -v133, v136, v135
	s_nop 1
	v_div_fmas_f32 v133, v133, v134, v136
	v_div_fixup_f32 v128, v133, v132, 1.0
	v_pk_mul_f32 v[96:97], v[96:97], v[128:129] op_sel_hi:[1,0]
	v_pk_mul_f32 v[98:99], v[98:99], v[128:129] op_sel_hi:[1,0]
	v_pk_mul_f32 v[100:101], v[100:101], v[128:129] op_sel_hi:[1,0]
	v_pk_mul_f32 v[102:103], v[102:103], v[128:129] op_sel_hi:[1,0]
	v_pk_mul_f32 v[104:105], v[104:105], v[128:129] op_sel_hi:[1,0]
	v_pk_mul_f32 v[106:107], v[106:107], v[128:129] op_sel_hi:[1,0]
	v_pk_mul_f32 v[108:109], v[108:109], v[128:129] op_sel_hi:[1,0]
	v_pk_mul_f32 v[110:111], v[110:111], v[128:129] op_sel_hi:[1,0]
	v_pk_fma_f32 v[112:113], v[80:81], v[96:97], v[112:113]
	v_pk_fma_f32 v[114:115], v[82:83], v[98:99], v[114:115]
	v_pk_fma_f32 v[116:117], v[84:85], v[100:101], v[116:117]
	v_pk_fma_f32 v[118:119], v[86:87], v[102:103], v[118:119]
	v_pk_fma_f32 v[120:121], v[88:89], v[104:105], v[120:121]
	v_pk_fma_f32 v[122:123], v[90:91], v[106:107], v[122:123]
	v_pk_fma_f32 v[124:125], v[92:93], v[108:109], v[124:125]
	v_pk_fma_f32 v[126:127], v[94:95], v[110:111], v[126:127]
	global_store_dwordx4 v4, v[112:115], s[40:41] offset:0 nt
	global_store_dwordx4 v4, v[116:119], s[40:41] offset:1024 nt
	global_store_dwordx4 v4, v[120:123], s[40:41] offset:2048 nt
	global_store_dwordx4 v4, v[124:127], s[40:41] offset:3072 nt
	s_waitcnt vmcnt(12)
	v_lshlrev_b32_e32 v96, 16, v64
	v_and_b32_e32 v97, 0xffff0000, v64
	v_lshlrev_b32_e32 v98, 16, v65
	v_and_b32_e32 v99, 0xffff0000, v65
	v_lshlrev_b32_e32 v100, 16, v66
	v_and_b32_e32 v101, 0xffff0000, v66
	v_lshlrev_b32_e32 v102, 16, v67
	v_and_b32_e32 v103, 0xffff0000, v67
	v_lshlrev_b32_e32 v104, 16, v68
	v_and_b32_e32 v105, 0xffff0000, v68
	v_lshlrev_b32_e32 v106, 16, v69
	v_and_b32_e32 v107, 0xffff0000, v69
	v_lshlrev_b32_e32 v108, 16, v70
	v_and_b32_e32 v109, 0xffff0000, v70
	v_lshlrev_b32_e32 v110, 16, v71
	v_and_b32_e32 v111, 0xffff0000, v71
	v_mul_f32_e32 v129, v97, v97
	v_mul_f32_e32 v130, v99, v99
	v_fmac_f32_e32 v129, v96, v96
	v_fmac_f32_e32 v130, v98, v98
	v_add_f32_e32 v128, v129, v130
	v_mul_f32_e32 v129, v101, v101
	v_mul_f32_e32 v130, v103, v103
	v_fmac_f32_e32 v129, v100, v100
	v_fmac_f32_e32 v130, v102, v102
	v_add_f32_e32 v129, v129, v130
	v_add_f32_e32 v128, v128, v129
	v_mul_f32_e32 v129, v105, v105
	v_mul_f32_e32 v130, v107, v107
	v_fmac_f32_e32 v129, v104, v104
	v_fmac_f32_e32 v130, v106, v106
	v_add_f32_e32 v129, v129, v130
	v_add_f32_e32 v128, v128, v129
	v_mul_f32_e32 v129, v109, v109
	v_mul_f32_e32 v130, v111, v111
	v_fmac_f32_e32 v129, v108, v108
	v_fmac_f32_e32 v130, v110, v110
	v_add_f32_e32 v129, v129, v130
	v_add_f32_e32 v128, v128, v129
	v_lshlrev_b32_e32 v112, 16, v72
	v_and_b32_e32 v113, 0xffff0000, v72
	v_lshlrev_b32_e32 v114, 16, v73
	v_and_b32_e32 v115, 0xffff0000, v73
	v_lshlrev_b32_e32 v116, 16, v74
	v_and_b32_e32 v117, 0xffff0000, v74
	v_lshlrev_b32_e32 v118, 16, v75
	v_and_b32_e32 v119, 0xffff0000, v75
	v_lshlrev_b32_e32 v120, 16, v76
	v_and_b32_e32 v121, 0xffff0000, v76
	v_lshlrev_b32_e32 v122, 16, v77
	v_and_b32_e32 v123, 0xffff0000, v77
	v_lshlrev_b32_e32 v124, 16, v78
	v_and_b32_e32 v125, 0xffff0000, v78
	v_lshlrev_b32_e32 v126, 16, v79
	v_and_b32_e32 v127, 0xffff0000, v79
	v_add_f32_dpp v128, v128, v128 quad_perm:[1,0,3,2] row_mask:0xf bank_mask:0xf
	s_nop 1
	v_add_f32_dpp v128, v128, v128 quad_perm:[2,3,0,1] row_mask:0xf bank_mask:0xf
	s_nop 1
	v_add_f32_dpp v128, v128, v128 row_half_mirror row_mask:0xf bank_mask:0xf
	s_nop 1
	v_add_f32_dpp v128, v128, v128 row_mirror row_mask:0xf bank_mask:0xf
	s_nop 0
	v_readlane_b32 s24, v128, 0
	v_readlane_b32 s25, v128, 16
	v_readlane_b32 s26, v128, 32
	v_readlane_b32 s27, v128, 48
	v_mov_b32_e32 v129, s24
	v_mov_b32_e32 v130, s26
	v_add_f32_e32 v129, s25, v129
	v_add_f32_e32 v130, s27, v130
	v_add_f32_e32 v128, v129, v130
	v_fmamk_f32 v128, v128, 0x3a800000, v143
	v_sqrt_f32_e32 v132, v128
	s_nop 0
	v_add_u32_e32 v133, -1, v132
	v_add_u32_e32 v134, 1, v132
	v_fma_f32 v135, -v133, v132, v128
	v_fma_f32 v136, -v134, v132, v128
	v_cmp_ge_f32_e64 s[20:21], 0, v135
	s_nop 1
	v_cndmask_b32_e64 v132, v132, v133, s[20:21]
	v_cmp_lt_f32_e64 s[20:21], 0, v136
	s_nop 1
	v_cndmask_b32_e64 v132, v132, v134, s[20:21]
	v_div_scale_f32 v133, s[20:21], v132, v132, 1.0
	v_rcp_f32_e32 v134, v133
	v_div_scale_f32 v135, vcc, 1.0, v132, 1.0
	v_fma_f32 v136, -v133, v134, 1.0
	v_fmac_f32_e32 v134, v136, v134
	v_mul_f32_e32 v136, v135, v134
	v_fma_f32 v137, -v133, v136, v135
	v_fmac_f32_e32 v136, v137, v134
	v_fma_f32 v133, -v133, v136, v135
	s_nop 1
	v_div_fmas_f32 v133, v133, v134, v136
	v_div_fixup_f32 v128, v133, v132, 1.0
	v_pk_mul_f32 v[96:97], v[96:97], v[128:129] op_sel_hi:[1,0]
	v_pk_mul_f32 v[98:99], v[98:99], v[128:129] op_sel_hi:[1,0]
	v_pk_mul_f32 v[100:101], v[100:101], v[128:129] op_sel_hi:[1,0]
	v_pk_mul_f32 v[102:103], v[102:103], v[128:129] op_sel_hi:[1,0]
	v_pk_mul_f32 v[104:105], v[104:105], v[128:129] op_sel_hi:[1,0]
	v_pk_mul_f32 v[106:107], v[106:107], v[128:129] op_sel_hi:[1,0]
	v_pk_mul_f32 v[108:109], v[108:109], v[128:129] op_sel_hi:[1,0]
	v_pk_mul_f32 v[110:111], v[110:111], v[128:129] op_sel_hi:[1,0]
	v_pk_fma_f32 v[112:113], v[80:81], v[96:97], v[112:113]
	v_pk_fma_f32 v[114:115], v[82:83], v[98:99], v[114:115]
	v_pk_fma_f32 v[116:117], v[84:85], v[100:101], v[116:117]
	v_pk_fma_f32 v[118:119], v[86:87], v[102:103], v[118:119]
	v_pk_fma_f32 v[120:121], v[88:89], v[104:105], v[120:121]
	v_pk_fma_f32 v[122:123], v[90:91], v[106:107], v[122:123]
	v_pk_fma_f32 v[124:125], v[92:93], v[108:109], v[124:125]
	v_pk_fma_f32 v[126:127], v[94:95], v[110:111], v[126:127]
	global_store_dwordx4 v4, v[112:115], s[42:43] offset:0 nt
	global_store_dwordx4 v4, v[116:119], s[42:43] offset:1024 nt
	global_store_dwordx4 v4, v[120:123], s[42:43] offset:2048 nt
	global_store_dwordx4 v4, v[124:127], s[42:43] offset:3072 nt
	s_lshl_b32 s0, s5, 2
	s_add_i32 s35, s35, s0
	s_cmp_lt_i32 s35, 0xc000
	s_cbranch_scc1 .Lp8_loop
